# w_in[1] conversion items in the barrier-5 wait reassigned: the scan+prep workgroups (measured to reach barrier 5 last) convert nothing, every other workgroup converts two tiles
# speedup vs baseline: 1.0027x; 1.0027x over previous
.Lgb5_wait:
.LBB0_776:
	s_or_b64 exec, exec, s[4:5]
	v_readlane_b32 s8, v255, 16
	v_readlane_b32 s9, v255, 17
	s_movk_i32 s10, 0x3000
	s_movk_i32 s11, 0x104
	s_mov_b32 s37, 0
	v_mov_b32_e32 v205, 0
	s_cmpk_lt_u32 s76, 0x80
	s_cbranch_scc1 .Lcv_none
	s_add_i32 s7, s76, 0x80
.Lcv_loop:
	s_lshl_b32 s0, s7, 6
	s_and_b32 s6, s0, 0x3c0
	s_lshl_b32 s0, s7, 2
	s_and_b32 s0, s0, 0xfc0
	s_add_i32 s36, s0, 0xfffffc00
	v_mov_b32_e32 v8, v207
	s_lshl_b64 s[0:1], s[36:37], 2
	s_add_u32 s0, s8, s0
	v_lshlrev_b32_e32 v0, 4, v8
	v_ashrrev_i32_e32 v6, 4, v8
	s_addc_u32 s1, s9, s1
	v_and_b32_e32 v204, 0xf0, v0
	v_lshl_add_u64 v[4:5], s[0:1], 0, v[204:205]
	v_add_u32_e32 v9, s6, v6
	v_mad_i64_i32 v[0:1], s[0:1], v9, s10, v[4:5]
	global_load_dwordx4 v[40:43], v[0:1], off nt
	v_add_u32_e32 v58, 16, v9
	v_mad_i64_i32 v[58:59], s[0:1], v58, s10, v[4:5]
	global_load_dwordx4 v[44:47], v[58:59], off nt
	v_add_u32_e32 v60, 32, v9
	v_mad_i64_i32 v[60:61], s[0:1], v60, s10, v[4:5]
	global_load_dwordx4 v[48:51], v[60:61], off nt
	v_add_u32_e32 v62, 48, v9
	v_mad_i64_i32 v[62:63], s[0:1], v62, s10, v[4:5]
	global_load_dwordx4 v[52:55], v[62:63], off nt
	v_mad_u64_u32 v[6:7], s[0:1], v6, s11, v[204:205]
	v_add_u32_e32 v7, 0x1040, v6
	v_ashrrev_i32_e32 v22, 3, v8
	s_waitcnt vmcnt(3)
	ds_write2_b32 v6, v40, v41 offset1:1
	ds_write2_b32 v6, v42, v43 offset0:2 offset1:3
	s_waitcnt vmcnt(2)
	ds_write2_b32 v7, v44, v45 offset1:1
	v_add_u32_e32 v0, 0x1048, v6
	ds_write2_b32 v0, v46, v47 offset1:1
	v_add_u32_e32 v7, 0x2080, v6
	s_waitcnt vmcnt(1)
	ds_write2_b32 v7, v48, v49 offset1:1
	v_add_u32_e32 v0, 0x2088, v6
	ds_write2_b32 v0, v50, v51 offset1:1
	v_add_u32_e32 v4, 0x30c0, v6
	s_lshl_b32 s0, s6, 1
	s_add_u32 s0, s58, s0
	s_addc_u32 s1, s59, 0
	s_waitcnt vmcnt(0)
	ds_write2_b32 v4, v52, v53 offset1:1
	v_add_u32_e32 v0, 0x30c8, v6
	ds_write2_b32 v0, v54, v55 offset1:1
	v_lshlrev_b32_e32 v0, 3, v8
	v_and_b32_e32 v0, 56, v0
	v_lshlrev_b32_e32 v204, 1, v0
	v_mul_u32_u24_e32 v0, 0x104, v0
	v_lshl_add_u32 v0, v22, 2, v0
	s_waitcnt lgkmcnt(0)
	s_barrier
	ds_read2_b32 v[6:7], v0 offset1:32
	ds_read2_b32 v[8:9], v0 offset0:65 offset1:97
	ds_read2_b32 v[10:11], v0 offset0:130 offset1:162
	ds_read2_b32 v[12:13], v0 offset0:195 offset1:227
	v_add_u32_e32 v0, 0x400, v0
	ds_read2_b32 v[14:15], v0 offset0:4 offset1:36
	ds_read2_b32 v[16:17], v0 offset0:69 offset1:101
	ds_read2_b32 v[18:19], v0 offset0:134 offset1:166
	ds_read2_b32 v[20:21], v0 offset0:199 offset1:231
	v_add_u32_e32 v22, s36, v22
	v_ashrrev_i32_e32 v23, 31, v22
	v_lshl_add_u64 v[4:5], s[0:1], 0, v[204:205]
	v_lshlrev_b64 v[24:25], 11, v[22:23]
	s_waitcnt lgkmcnt(6)
	v_cvt_pk_bf16_f32 v0, v6, v8
	s_waitcnt lgkmcnt(4)
	v_cvt_pk_bf16_f32 v1, v10, v12
	s_waitcnt lgkmcnt(2)
	v_cvt_pk_bf16_f32 v2, v14, v16
	s_waitcnt lgkmcnt(0)
	v_cvt_pk_bf16_f32 v3, v18, v20
	v_lshl_add_u64 v[24:25], v[4:5], 0, v[24:25]
	v_add_u32_e32 v6, 32, v22
	global_store_dwordx4 v[24:25], v[0:3], off
	s_nop 1
	v_cvt_pk_bf16_f32 v0, v7, v9
	v_ashrrev_i32_e32 v7, 31, v6
	v_lshlrev_b64 v[6:7], 11, v[6:7]
	v_cvt_pk_bf16_f32 v1, v11, v13
	v_cvt_pk_bf16_f32 v2, v15, v17
	v_cvt_pk_bf16_f32 v3, v19, v21
	v_lshl_add_u64 v[4:5], v[4:5], 0, v[6:7]
	global_store_dwordx4 v[4:5], v[0:3], off
	s_barrier
	s_addk_i32 s7, 0x180
	s_cmpk_lt_i32 s7, 0x400
	s_cbranch_scc1 .Lcv_loop
.Lcv_none:
	s_waitcnt vmcnt(0)
	s_barrier
	s_mov_b64 s[12:13], exec
	v_readlane_b32 s0, v255, 1
	v_readlane_b32 s1, v255, 2
	s_nop 1
	s_mov_b64 exec, s[0:1]
	s_cbranch_execz .Lthr0_b5
	v_readlane_b32 s98, v255, 5
	v_readlane_b32 s99, v255, 6
	v_mov_b32_e32 v19, 0x10000
	ds_read_b32 v2, v19
	s_lshl_b32 s0, s3, 3
	s_add_i32 s0, s0, 0x380
	v_mov_b32_e32 v3, s0
	v_mov_b32_e32 v4, 1
	s_nop 2
	global_atomic_add v3, v3, v4, s[98:99] sc0
	s_waitcnt vmcnt(0) lgkmcnt(0)
	v_add_u32_e32 v3, 1, v3
	v_cmp_eq_u32_e32 vcc, v3, v2
	s_cbranch_vccz .Lcv_sig_done
	buffer_wbl2 sc1
	s_waitcnt vmcnt(0)
	v_mov_b32_e32 v3, 0x3c0
	global_atomic_add v3, v4, s[98:99]
